# cache policy: nt on retention's final-use q/k/v tile loads and gate reads
# speedup vs baseline: 1.0021x; 1.0021x over previous
; #define LAS __attribute__((address_space(3)))
; __device__ __forceinline__ unsigned cvt_pk_bf16(float lo, float hi) { unsigned r; asm("v_cvt_pk_bf16_f32 %0, %1, %2" : "=v"(r) : "v"(lo), "v"(hi)); return r; }
; __device__ __forceinline__ float sigmoidf_(float x) { return 1.f / (1.f + expf(-x)); }
; __device__ __forceinline__ float bf2f(unsigned short x) { return __uint_as_float(((unsigned)x) << 16); }
; __device__ __forceinline__ void ret_out_unit(const Frame& F, int l, int unit) {
;     ...
;     for (int ks = 0; ks < 2; ++ks) {
;         const bf16x8 a = *(const LAS bf16x8*)(L + RL_Q + ((i0 + fr) * 64 + 32 * ks + fq * 8) * 2);
; #pragma unroll
;         for (int dt = 0; dt < 4; ++dt) { const bf16x8 bb = *(const LAS bf16x8*)(L + RL_ST + ((16 * dt + fr) * 64 + 32 * ks + fq * 8) * 2);
;             acc2[dt] = __builtin_amdgcn_mfma_f32_16x16x32_bf16(a, bb, acc2[dt], 0, 0, 0); }
;     }
;     const float* gnw = F.in[5] + l * 256 + h * 64;
; #pragma unroll
;     for (int j = 0; j < 4; ++j) {
;         const int i = i0 + fq * 4 + j; const float qd = expf((float)(i + 1) * lg);
;         float o[4], sm = 0.f;
; #pragma unroll
;         for (int dt = 0; dt < 4; ++dt) { o[dt] = acc1[dt][j] + qd * acc2[dt][j]; sm += o[dt]; }
;         sm += __shfl_xor(sm, 1); sm += __shfl_xor(sm, 2); sm += __shfl_xor(sm, 4); sm += __shfl_xor(sm, 8);
;         const float mean = sm * (1.f / 64.f); float vs = 0.f;
; #pragma unroll
;         for (int dt = 0; dt < 4; ++dt) { o[dt] -= mean; vs += o[dt] * o[dt]; }
;         vs += __shfl_xor(vs, 1); vs += __shfl_xor(vs, 2); vs += __shfl_xor(vs, 4); vs += __shfl_xor(vs, 8);
;         const float rstd = 1.f / sqrtf(vs * (1.f / 64.f) + LN_EPS);
;         const size_t tok = (size_t)b * S + n * 128 + i;
; #pragma unroll
;         for (int dt = 0; dt < 4; ++dt) { const int e = 16 * dt + fr;
;             const float rg = bf2f(((const bf16*)(F.ws + WS_RG))[tok * 256 + h * 64 + e]);
;             const float yv = o[dt] * rstd * gnw[e] * (rg * sigmoidf_(rg));
;             ((bf16*)(F.ws + WS_Y))[tok * D + h * 64 + e] = (bf16)(cvt_pk_bf16(yv, yv) & 0xffffu); }
.LBB0_1559:
	v_add_u32_e32 v30, v142, v129
	ds_read_b128 v[18:21], v30
	v_readlane_b32 s3, v249, 35
	v_readlane_b32 s10, v249, 36
	v_readlane_b32 s11, v249, 37
	v_add_u32_e32 v22, s6, v147
	v_add_u32_e32 v26, s3, v147
	v_add_u32_e32 v34, s10, v147
	v_add_u32_e32 v38, s11, v147
	ds_read_b128 v[22:25], v22
	ds_read_b128 v[26:29], v26
	ds_read_b128 v[30:33], v30 offset:64
	ds_read_b128 v[34:37], v34
	ds_read_b128 v[38:41], v38
	s_waitcnt lgkmcnt(4)
	v_mfma_f32_16x16x32_bf16 v[22:25], v[18:21], v[22:25], 0
	v_add_u32_e32 v42, s3, v148
	ds_read_b128 v[42:45], v42
	v_add_u32_e32 v46, s10, v148
	s_waitcnt lgkmcnt(4)
	v_mfma_f32_16x16x32_bf16 v[26:29], v[18:21], v[26:29], 0
	s_lshl_b32 s3, s79, 7
	s_waitcnt lgkmcnt(2)
	v_mfma_f32_16x16x32_bf16 v[34:37], v[18:21], v[34:37], 0
	s_waitcnt lgkmcnt(1)
	v_mfma_f32_16x16x32_bf16 v[38:41], v[18:21], v[38:41], 0
	v_add_u32_e32 v18, s6, v148
	ds_read_b128 v[18:21], v18
	s_waitcnt lgkmcnt(0)
	v_mfma_f32_16x16x32_bf16 v[18:21], v[30:33], v[18:21], v[22:25]
	v_mfma_f32_16x16x32_bf16 v[22:25], v[30:33], v[42:45], v[26:29]
	v_add_u32_e32 v42, s11, v148
	ds_read_b128 v[42:45], v42
	s_lshl_b64 s[10:11], s[72:73], 11
	ds_read_b128 v[26:29], v46
	s_waitcnt lgkmcnt(0)
	v_mfma_f32_16x16x32_bf16 v[26:29], v[30:33], v[26:29], v[34:37]
	s_nop 2
	v_and_b32_e32 v35, 64, v225
	v_xor_b32_e32 v34, 1, v225
	v_add_u32_e32 v35, 64, v35
	v_mfma_f32_16x16x32_bf16 v[30:33], v[30:33], v[42:45], v[38:41]
	v_cmp_lt_i32_e32 vcc, v34, v35
	s_or_b64 s[44:45], s[10:11], s[34:35]
	s_add_u32 s46, s7, s3
	v_mul_f32_e32 v38, s78, v143
	v_mul_f32_e32 v37, 0x3fb8aa3b, v38
	v_fma_f32 v39, v38, s17, -v37
	v_rndne_f32_e32 v40, v37
	v_fmac_f32_e32 v39, 0x32a5705f, v38
	v_sub_f32_e32 v37, v37, v40
	v_add_f32_e32 v37, v37, v39
	v_exp_f32_e32 v39, v37
	v_cvt_i32_f32_e32 v40, v40
	v_cndmask_b32_e32 v34, v225, v34, vcc
	v_lshlrev_b32_e32 v36, 2, v34
	v_xor_b32_e32 v34, 2, v225
	v_cmp_lt_i32_e32 vcc, v34, v35
	v_ldexp_f32 v39, v39, v40
	s_addc_u32 s47, s8, 0
	v_cndmask_b32_e32 v34, v225, v34, vcc
	v_cmp_ngt_f32_e32 vcc, s21, v38
	v_lshlrev_b32_e32 v37, 2, v34
	v_xor_b32_e32 v34, 4, v225
	v_cndmask_b32_e32 v39, 0, v39, vcc
	v_cmp_nlt_f32_e32 vcc, s22, v38
	s_add_u32 s42, s9, s3
	s_addc_u32 s43, s74, 0
	v_cndmask_b32_e32 v38, v230, v39, vcc
	v_fmac_f32_e32 v14, v38, v18
	v_add_f32_e32 v18, 0, v14
	v_fmac_f32_e32 v10, v38, v22
	v_add_f32_e32 v18, v18, v10
	v_fmac_f32_e32 v6, v38, v26
	v_add_f32_e32 v18, v18, v6
	v_fmac_f32_e32 v2, v38, v30
	v_add_f32_e32 v18, v18, v2
	ds_bpermute_b32 v22, v36, v18
	v_cmp_lt_i32_e32 vcc, v34, v35
	s_lshl_b32 s34, s79, 8
	v_lshl_add_u64 v[42:43], v[138:139], 0, s[34:35]
	v_cndmask_b32_e32 v26, v225, v34, vcc
	v_lshlrev_b32_e32 v30, 2, v26
	v_xor_b32_e32 v26, 8, v225
	v_cmp_lt_i32_e32 vcc, v26, v35
	v_lshl_add_u64 v[34:35], s[44:45], 0, v[130:131]
	s_waitcnt lgkmcnt(0)
	v_add_f32_e32 v18, v18, v22
	v_lshlrev_b64 v[40:41], 9, v[34:35]
	ds_bpermute_b32 v22, v37, v18
	v_lshl_add_u64 v[40:41], s[46:47], 0, v[40:41]
	v_cndmask_b32_e32 v26, v225, v26, vcc
	v_lshl_add_u64 v[40:41], v[40:41], 0, v[198:199]
	v_lshlrev_b32_e32 v38, 2, v26
	global_load_ushort v26, v[40:41], off nt
	global_load_ushort v44, v[40:41], off offset:32 nt
	global_load_ushort v48, v[40:41], off offset:64 nt
	s_waitcnt lgkmcnt(0)
	v_add_f32_e32 v18, v18, v22
	ds_bpermute_b32 v22, v30, v18
	global_load_ushort v40, v[40:41], off offset:96 nt
	v_lshlrev_b64 v[34:35], 11, v[34:35]
	v_lshl_add_u64 v[34:35], s[42:43], 0, v[34:35]
	v_lshl_add_u64 v[34:35], v[34:35], 0, v[198:199]
	s_waitcnt lgkmcnt(0)
	v_add_f32_e32 v18, v18, v22
	ds_bpermute_b32 v22, v38, v18
	s_add_i32 s77, s77, s81
	s_cmpk_gt_i32 s77, 0x1ff
	s_waitcnt lgkmcnt(0)
	v_add_f32_e32 v18, v18, v22
	v_fmac_f32_e32 v10, 0xbc800000, v18
	v_fmac_f32_e32 v14, 0xbc800000, v18
	v_mul_f32_e32 v22, v10, v10
	v_fmac_f32_e32 v22, v14, v14
	v_fmac_f32_e32 v6, 0xbc800000, v18
	v_fmac_f32_e32 v22, v6, v6
	v_fmac_f32_e32 v2, 0xbc800000, v18
	v_fmac_f32_e32 v22, v2, v2
	ds_bpermute_b32 v18, v36, v22
	s_waitcnt lgkmcnt(0)
	v_add_f32_e32 v22, v22, v18
	ds_bpermute_b32 v39, v37, v22
	global_load_dword v18, v[42:43], off
	s_waitcnt lgkmcnt(0)
	v_add_f32_e32 v22, v22, v39
	ds_bpermute_b32 v39, v30, v22
	s_waitcnt lgkmcnt(0)
	v_add_f32_e32 v22, v22, v39
	ds_bpermute_b32 v39, v38, v22
	s_waitcnt lgkmcnt(0)
	v_add_f32_e32 v22, v22, v39
	v_fmamk_f32 v22, v22, 0x3c800000, v226
	v_mul_f32_e32 v39, 0x4f800000, v22
	v_cmp_gt_f32_e32 vcc, s2, v22
	s_waitcnt vmcnt(4)
	v_lshlrev_b32_e32 v41, 16, v26
	v_cndmask_b32_e32 v39, v22, v39, vcc
	v_sqrt_f32_e32 v22, v39
	v_mul_f32_e32 v26, 0xbfb8aa3b, v41
	v_add_u32_e32 v45, -1, v22
	v_fma_f32 v46, -v45, v22, v39
	v_cmp_ge_f32_e64 s[40:41], 0, v46
	v_add_u32_e32 v46, 1, v22
	s_nop 0
	v_cndmask_b32_e64 v45, v22, v45, s[40:41]
	v_fma_f32 v22, -v46, v22, v39
	v_cmp_lt_f32_e64 s[40:41], 0, v22
	s_nop 1
	v_cndmask_b32_e64 v22, v45, v46, s[40:41]
	v_mul_f32_e32 v45, 0x37800000, v22
	v_cndmask_b32_e32 v45, v22, v45, vcc
	global_load_dword v22, v[42:43], off offset:64
	v_cmp_class_f32_e32 vcc, v39, v227
	s_nop 1
	v_cndmask_b32_e32 v39, v45, v39, vcc
	v_div_scale_f32 v45, s[10:11], v39, v39, 1.0
	v_rcp_f32_e32 v46, v45
	s_nop 0
	v_fma_f32 v47, -v45, v46, 1.0
	v_fmac_f32_e32 v46, v47, v46
	v_div_scale_f32 v47, vcc, 1.0, v39, 1.0
	v_mul_f32_e32 v49, v47, v46
	v_fma_f32 v50, -v45, v49, v47
	v_fmac_f32_e32 v49, v50, v46
	v_fma_f32 v45, -v45, v49, v47
	v_div_fmas_f32 v45, v45, v46, v49
	v_fma_f32 v46, v41, s83, -v26
	v_rndne_f32_e32 v47, v26
	v_div_fixup_f32 v45, v45, v39, 1.0
	global_load_dword v39, v[42:43], off offset:128
	v_fmac_f32_e32 v46, 0xb2a5705f, v41
	v_sub_f32_e32 v26, v26, v47
	v_add_f32_e32 v26, v26, v46
	v_exp_f32_e32 v26, v26
	v_cvt_i32_f32_e32 v46, v47
	v_cmp_nlt_f32_e32 vcc, s92, v41
	v_mul_f32_e32 v14, v14, v45
	v_mul_f32_e32 v10, v10, v45
	v_ldexp_f32 v26, v26, v46
	v_cndmask_b32_e32 v26, 0, v26, vcc
	v_cmp_ngt_f32_e32 vcc, s93, v41
	v_mul_f32_e32 v6, v6, v45
	v_mul_f32_e32 v2, v2, v45
	v_cndmask_b32_e32 v26, v230, v26, vcc
	v_add_f32_e32 v46, 1.0, v26
	v_div_scale_f32 v47, s[10:11], v46, v46, 1.0
	v_rcp_f32_e32 v49, v47
	global_load_dword v26, v[42:43], off offset:192
	s_waitcnt vmcnt(3)
; __device__ __forceinline__ unsigned cvt_pk_bf16(float lo, float hi) { unsigned r; asm("v_cvt_pk_bf16_f32 %0, %1, %2" : "=v"(r) : "v"(lo), "v"(hi)); return r; }
; __device__ __forceinline__ float sigmoidf_(float x) { return 1.f / (1.f + expf(-x)); }
; __device__ __forceinline__ float bf2f(unsigned short x) { return __uint_as_float(((unsigned)x) << 16); }
; __device__ __forceinline__ void ret_out_unit(const Frame& F, int l, int unit) {
;     ...
;     for (int j = 0; j < 4; ++j) {
;         const int i = i0 + fq * 4 + j; const float qd = expf((float)(i + 1) * lg);
;         float o[4], sm = 0.f;
; #pragma unroll
;         for (int dt = 0; dt < 4; ++dt) { o[dt] = acc1[dt][j] + qd * acc2[dt][j]; sm += o[dt]; }
;         sm += __shfl_xor(sm, 1); sm += __shfl_xor(sm, 2); sm += __shfl_xor(sm, 4); sm += __shfl_xor(sm, 8);
;         const float mean = sm * (1.f / 64.f); float vs = 0.f;
; #pragma unroll
;         for (int dt = 0; dt < 4; ++dt) { o[dt] -= mean; vs += o[dt] * o[dt]; }
;         vs += __shfl_xor(vs, 1); vs += __shfl_xor(vs, 2); vs += __shfl_xor(vs, 4); vs += __shfl_xor(vs, 8);
;         const float rstd = 1.f / sqrtf(vs * (1.f / 64.f) + LN_EPS);
;         const size_t tok = (size_t)b * S + n * 128 + i;
; #pragma unroll
;         for (int dt = 0; dt < 4; ++dt) { const int e = 16 * dt + fr;
;             const float rg = bf2f(((const bf16*)(F.ws + WS_RG))[tok * 256 + h * 64 + e]);
;             const float yv = o[dt] * rstd * gnw[e] * (rg * sigmoidf_(rg));
;             ((bf16*)(F.ws + WS_Y))[tok * D + h * 64 + e] = (bf16)(cvt_pk_bf16(yv, yv) & 0xffffu); }
	v_mul_f32_e32 v14, v18, v14
	v_fma_f32 v42, -v47, v49, 1.0
	v_fmac_f32_e32 v49, v42, v49
	v_div_scale_f32 v42, vcc, 1.0, v46, 1.0
	v_mul_f32_e32 v43, v42, v49
	v_fma_f32 v50, -v47, v43, v42
	v_fmac_f32_e32 v43, v50, v49
	v_fma_f32 v42, -v47, v43, v42
	v_div_fmas_f32 v42, v42, v49, v43
	v_div_fixup_f32 v42, v42, v46, 1.0
	v_mul_f32_e32 v41, v42, v41
	v_lshlrev_b32_e32 v42, 16, v44
	v_mul_f32_e32 v43, 0xbfb8aa3b, v42
	v_fma_f32 v44, v42, s83, -v43
	v_rndne_f32_e32 v46, v43
	v_fmac_f32_e32 v44, 0xb2a5705f, v42
	v_sub_f32_e32 v43, v43, v46
	v_add_f32_e32 v43, v43, v44
	v_exp_f32_e32 v43, v43
	v_cvt_i32_f32_e32 v44, v46
	v_mul_f32_e32 v14, v41, v14
	v_cmp_nlt_f32_e32 vcc, s92, v42
	v_cvt_pk_bf16_f32 v14, v14, v14
	v_ldexp_f32 v41, v43, v44
	global_store_short v[34:35], v14, off
	v_cndmask_b32_e32 v41, 0, v41, vcc
	v_cmp_ngt_f32_e32 vcc, s93, v42
	s_waitcnt vmcnt(3)
	v_mul_f32_e32 v10, v22, v10
	v_cndmask_b32_e32 v41, v230, v41, vcc
	v_add_f32_e32 v41, 1.0, v41
	v_div_scale_f32 v43, s[10:11], v41, v41, 1.0
	v_rcp_f32_e32 v44, v43
	s_waitcnt vmcnt(2)
	v_mul_f32_e32 v6, v39, v6
	v_fma_f32 v14, -v43, v44, 1.0
	v_fmac_f32_e32 v44, v14, v44
	v_div_scale_f32 v14, vcc, 1.0, v41, 1.0
	v_mul_f32_e32 v46, v14, v44
	v_fma_f32 v47, -v43, v46, v14
	v_fmac_f32_e32 v46, v47, v44
	v_fma_f32 v14, -v43, v46, v14
	v_div_fmas_f32 v14, v14, v44, v46
	v_div_fixup_f32 v14, v14, v41, 1.0
	v_lshlrev_b32_e32 v41, 16, v48
	v_mul_f32_e32 v43, 0xbfb8aa3b, v41
	v_fma_f32 v44, v41, s83, -v43
	v_rndne_f32_e32 v46, v43
	v_fmac_f32_e32 v44, 0xb2a5705f, v41
	v_sub_f32_e32 v43, v43, v46
	v_add_f32_e32 v43, v43, v44
	v_exp_f32_e32 v43, v43
	v_cvt_i32_f32_e32 v44, v46
	v_mul_f32_e32 v14, v14, v42
	v_mul_f32_e32 v10, v14, v10
	v_cmp_nlt_f32_e32 vcc, s92, v41
	v_ldexp_f32 v14, v43, v44
	v_cvt_pk_bf16_f32 v10, v10, v10
	global_store_short v[34:35], v10, off offset:32
	v_cndmask_b32_e32 v14, 0, v14, vcc
	v_cmp_ngt_f32_e32 vcc, s93, v41
	s_waitcnt vmcnt(2)
	v_mul_f32_e32 v2, v2, v26
	v_cndmask_b32_e32 v14, v230, v14, vcc
	v_add_f32_e32 v14, 1.0, v14
	v_div_scale_f32 v42, s[10:11], v14, v14, 1.0
	v_rcp_f32_e32 v43, v42
	s_nop 0
	v_fma_f32 v10, -v42, v43, 1.0
	v_fmac_f32_e32 v43, v10, v43
	v_div_scale_f32 v10, vcc, 1.0, v14, 1.0
	v_mul_f32_e32 v44, v10, v43
	v_fma_f32 v46, -v42, v44, v10
	v_fmac_f32_e32 v44, v46, v43
	v_fma_f32 v10, -v42, v44, v10
	v_mul_f32_e32 v42, s78, v144
	v_div_fmas_f32 v10, v10, v43, v44
	v_mul_f32_e32 v43, 0x3fb8aa3b, v42
	v_fma_f32 v44, v42, s17, -v43
	v_rndne_f32_e32 v46, v43
	v_fmac_f32_e32 v44, 0x32a5705f, v42
	v_sub_f32_e32 v43, v43, v46
	v_add_f32_e32 v43, v43, v44
	v_exp_f32_e32 v43, v43
	v_cvt_i32_f32_e32 v44, v46
	v_div_fixup_f32 v10, v10, v14, 1.0
	v_mul_f32_e32 v10, v10, v41
	v_mul_f32_e32 v6, v6, v10
	v_ldexp_f32 v10, v43, v44
	v_cmp_ngt_f32_e32 vcc, s21, v42
	v_cvt_pk_bf16_f32 v6, v6, v6
	global_store_short v[34:35], v6, off offset:64
	s_nop 0
	v_cndmask_b32_e32 v10, 0, v10, vcc
	v_cmp_nlt_f32_e32 vcc, s22, v42
	s_nop 1
	v_cndmask_b32_e32 v10, v230, v10, vcc
	v_fmac_f32_e32 v15, v10, v19
	v_add_f32_e32 v14, 0, v15
	v_fmac_f32_e32 v11, v10, v23
	v_add_f32_e32 v14, v14, v11
	v_fmac_f32_e32 v7, v10, v27
	v_add_f32_e32 v14, v14, v7
	v_fmac_f32_e32 v3, v10, v31
	v_add_f32_e32 v10, v14, v3
	ds_bpermute_b32 v14, v36, v10
	v_lshlrev_b32_e32 v19, 16, v40
	v_lshl_add_u64 v[40:41], s[44:45], 0, v[132:133]
	v_mul_f32_e32 v23, 0xbfb8aa3b, v19
	v_lshlrev_b64 v[42:43], 9, v[40:41]
	s_waitcnt lgkmcnt(0)
	v_add_f32_e32 v10, v10, v14
	ds_bpermute_b32 v14, v37, v10
	v_fma_f32 v27, v19, s83, -v23
	v_rndne_f32_e32 v31, v23
	v_lshl_add_u64 v[42:43], s[46:47], 0, v[42:43]
	v_fmac_f32_e32 v27, 0xb2a5705f, v19
	s_waitcnt lgkmcnt(0)
	v_add_f32_e32 v10, v10, v14
	ds_bpermute_b32 v14, v30, v10
	v_sub_f32_e32 v23, v23, v31
	v_lshl_add_u64 v[42:43], v[42:43], 0, v[198:199]
	v_add_f32_e32 v23, v23, v27
	global_load_ushort v27, v[42:43], off nt
	global_load_ushort v45, v[42:43], off offset:32 nt
	s_waitcnt lgkmcnt(0)
	v_add_f32_e32 v10, v10, v14
	ds_bpermute_b32 v14, v38, v10
	v_exp_f32_e32 v23, v23
	v_cvt_i32_f32_e32 v31, v31
	v_cmp_nlt_f32_e32 vcc, s92, v19
	s_waitcnt lgkmcnt(0)
	v_add_f32_e32 v10, v10, v14
	v_fmac_f32_e32 v11, 0xbc800000, v10
	v_fmac_f32_e32 v15, 0xbc800000, v10
	v_mul_f32_e32 v14, v11, v11
	v_fmac_f32_e32 v14, v15, v15
	v_fmac_f32_e32 v7, 0xbc800000, v10
	v_fmac_f32_e32 v14, v7, v7
	v_fmac_f32_e32 v3, 0xbc800000, v10
	v_fmac_f32_e32 v14, v3, v3
	ds_bpermute_b32 v10, v36, v14
	v_ldexp_f32 v6, v23, v31
	v_cndmask_b32_e32 v6, 0, v6, vcc
	v_cmp_ngt_f32_e32 vcc, s93, v19
	s_waitcnt lgkmcnt(0)
	v_add_f32_e32 v10, v14, v10
	ds_bpermute_b32 v14, v37, v10
	v_cndmask_b32_e32 v6, v230, v6, vcc
	v_add_f32_e32 v6, 1.0, v6
	v_div_scale_f32 v23, s[10:11], v6, v6, 1.0
	s_waitcnt lgkmcnt(0)
	v_add_f32_e32 v10, v10, v14
	ds_bpermute_b32 v14, v30, v10
	v_rcp_f32_e32 v31, v23
	s_waitcnt lgkmcnt(0)
	v_add_f32_e32 v10, v10, v14
	ds_bpermute_b32 v14, v38, v10
	v_fma_f32 v44, -v23, v31, 1.0
	v_fmac_f32_e32 v31, v44, v31
	v_div_scale_f32 v44, vcc, 1.0, v6, 1.0
	s_waitcnt lgkmcnt(0)
; __device__ __forceinline__ unsigned cvt_pk_bf16(float lo, float hi) { unsigned r; asm("v_cvt_pk_bf16_f32 %0, %1, %2" : "=v"(r) : "v"(lo), "v"(hi)); return r; }
; __device__ __forceinline__ float sigmoidf_(float x) { return 1.f / (1.f + expf(-x)); }
; __device__ __forceinline__ float bf2f(unsigned short x) { return __uint_as_float(((unsigned)x) << 16); }
; __device__ __forceinline__ void ret_out_unit(const Frame& F, int l, int unit) {
;     ...
;     for (int j = 0; j < 4; ++j) {
;         const int i = i0 + fq * 4 + j; const float qd = expf((float)(i + 1) * lg);
;         float o[4], sm = 0.f;
; #pragma unroll
;         for (int dt = 0; dt < 4; ++dt) { o[dt] = acc1[dt][j] + qd * acc2[dt][j]; sm += o[dt]; }
;         sm += __shfl_xor(sm, 1); sm += __shfl_xor(sm, 2); sm += __shfl_xor(sm, 4); sm += __shfl_xor(sm, 8);
;         const float mean = sm * (1.f / 64.f); float vs = 0.f;
; #pragma unroll
;         for (int dt = 0; dt < 4; ++dt) { o[dt] -= mean; vs += o[dt] * o[dt]; }
;         vs += __shfl_xor(vs, 1); vs += __shfl_xor(vs, 2); vs += __shfl_xor(vs, 4); vs += __shfl_xor(vs, 8);
;         const float rstd = 1.f / sqrtf(vs * (1.f / 64.f) + LN_EPS);
;         const size_t tok = (size_t)b * S + n * 128 + i;
; #pragma unroll
;         for (int dt = 0; dt < 4; ++dt) { const int e = 16 * dt + fr;
;             const float rg = bf2f(((const bf16*)(F.ws + WS_RG))[tok * 256 + h * 64 + e]);
;             const float yv = o[dt] * rstd * gnw[e] * (rg * sigmoidf_(rg));
;             ((bf16*)(F.ws + WS_Y))[tok * D + h * 64 + e] = (bf16)(cvt_pk_bf16(yv, yv) & 0xffffu); }
	v_add_f32_e32 v10, v10, v14
	v_fmamk_f32 v10, v10, 0x3c800000, v226
	v_mul_f32_e32 v46, v44, v31
	v_mul_f32_e32 v14, 0x4f800000, v10
	v_cmp_gt_f32_e64 s[40:41], s2, v10
	v_fma_f32 v47, -v23, v46, v44
	v_fmac_f32_e32 v46, v47, v31
	v_cndmask_b32_e64 v10, v10, v14, s[40:41]
	v_sqrt_f32_e32 v14, v10
	v_fma_f32 v23, -v23, v46, v44
	v_div_fmas_f32 v23, v23, v31, v46
	v_div_fixup_f32 v6, v23, v6, 1.0
	v_mul_f32_e32 v6, v6, v19
	v_add_u32_e32 v19, -1, v14
	v_fma_f32 v23, -v19, v14, v10
	v_cmp_ge_f32_e32 vcc, 0, v23
	v_add_u32_e32 v23, 1, v14
	v_mul_f32_e32 v2, v2, v6
	v_cndmask_b32_e32 v19, v14, v19, vcc
	v_fma_f32 v14, -v23, v14, v10
	v_cmp_lt_f32_e32 vcc, 0, v14
	v_cvt_pk_bf16_f32 v2, v2, v2
	global_store_short v[34:35], v2, off offset:96
	s_nop 0
	v_cndmask_b32_e32 v14, v19, v23, vcc
	v_mul_f32_e32 v19, 0x37800000, v14
	v_cndmask_b32_e64 v14, v14, v19, s[40:41]
	v_cmp_class_f32_e32 vcc, v10, v227
	s_nop 1
	v_cndmask_b32_e32 v10, v14, v10, vcc
	v_div_scale_f32 v14, s[10:11], v10, v10, 1.0
	v_rcp_f32_e32 v19, v14
	v_div_scale_f32 v6, vcc, 1.0, v10, 1.0
	v_fma_f32 v2, -v14, v19, 1.0
	v_fmac_f32_e32 v19, v2, v19
	global_load_ushort v2, v[42:43], off offset:64 nt
	v_mul_f32_e32 v23, v6, v19
	v_fma_f32 v31, -v14, v23, v6
	v_fmac_f32_e32 v23, v31, v19
	v_fma_f32 v6, -v14, v23, v6
	global_load_ushort v31, v[42:43], off offset:96 nt
	s_waitcnt vmcnt(4)
	v_lshlrev_b32_e32 v14, 16, v27
	v_mul_f32_e32 v27, 0xbfb8aa3b, v14
	v_fma_f32 v34, v14, s83, -v27
	v_rndne_f32_e32 v35, v27
	v_fmac_f32_e32 v34, 0xb2a5705f, v14
	v_sub_f32_e32 v27, v27, v35
	v_add_f32_e32 v27, v27, v34
	v_exp_f32_e32 v27, v27
	v_cvt_i32_f32_e32 v42, v35
	v_div_fmas_f32 v6, v6, v19, v23
	v_div_fixup_f32 v19, v6, v10, 1.0
	v_cmp_nlt_f32_e32 vcc, s92, v14
	v_ldexp_f32 v6, v27, v42
	v_lshlrev_b64 v[34:35], 11, v[40:41]
	v_cndmask_b32_e32 v6, 0, v6, vcc
	v_cmp_ngt_f32_e32 vcc, s93, v14
	v_mul_f32_e32 v15, v15, v19
	v_lshl_add_u64 v[34:35], s[42:43], 0, v[34:35]
	v_cndmask_b32_e32 v6, v230, v6, vcc
	v_add_f32_e32 v6, 1.0, v6
	v_div_scale_f32 v10, s[10:11], v6, v6, 1.0
	v_rcp_f32_e32 v23, v10
	v_mul_f32_e32 v15, v18, v15
	v_fma_f32 v27, -v10, v23, 1.0
	v_fmac_f32_e32 v23, v27, v23
	v_div_scale_f32 v27, vcc, 1.0, v6, 1.0
	v_mul_f32_e32 v40, v27, v23
	v_fma_f32 v41, -v10, v40, v27
	v_fmac_f32_e32 v40, v41, v23
	v_fma_f32 v10, -v10, v40, v27
	v_div_fmas_f32 v10, v10, v23, v40
	v_div_fixup_f32 v6, v10, v6, 1.0
	s_waitcnt vmcnt(3)
	v_lshlrev_b32_e32 v10, 16, v45
	v_mul_f32_e32 v6, v6, v14
	v_mul_f32_e32 v14, 0xbfb8aa3b, v10
	v_fma_f32 v23, v10, s83, -v14
	v_rndne_f32_e32 v27, v14
	v_fmac_f32_e32 v23, 0xb2a5705f, v10
	v_sub_f32_e32 v14, v14, v27
	v_add_f32_e32 v14, v14, v23
	v_exp_f32_e32 v23, v14
	v_cvt_i32_f32_e32 v27, v27
	v_cmp_nlt_f32_e32 vcc, s92, v10
	v_mul_f32_e32 v6, v6, v15
	v_lshl_add_u64 v[14:15], v[34:35], 0, v[198:199]
	v_ldexp_f32 v23, v23, v27
	v_cndmask_b32_e32 v23, 0, v23, vcc
	v_cmp_ngt_f32_e32 vcc, s93, v10
	v_cvt_pk_bf16_f32 v6, v6, v6
	global_store_short v[14:15], v6, off
	v_mul_f32_e32 v6, v11, v19
	v_cndmask_b32_e32 v23, v230, v23, vcc
	v_add_f32_e32 v23, 1.0, v23
	v_div_scale_f32 v27, s[10:11], v23, v23, 1.0
	v_rcp_f32_e32 v34, v27
	v_mul_f32_e32 v6, v22, v6
	v_fma_f32 v11, -v27, v34, 1.0
	v_fmac_f32_e32 v34, v11, v34
	v_div_scale_f32 v11, vcc, 1.0, v23, 1.0
	v_mul_f32_e32 v35, v11, v34
	v_fma_f32 v40, -v27, v35, v11
	v_fmac_f32_e32 v35, v40, v34
	v_fma_f32 v11, -v27, v35, v11
	v_div_fmas_f32 v11, v11, v34, v35
	v_div_fixup_f32 v11, v11, v23, 1.0
	v_mul_f32_e32 v10, v11, v10
	s_waitcnt vmcnt(2)
	v_lshlrev_b32_e32 v2, 16, v2
	v_mul_f32_e32 v23, 0xbfb8aa3b, v2
	v_fma_f32 v27, v2, s83, -v23
	v_rndne_f32_e32 v34, v23
	v_fmac_f32_e32 v27, 0xb2a5705f, v2
	v_sub_f32_e32 v23, v23, v34
	v_add_f32_e32 v23, v23, v27
	v_exp_f32_e32 v23, v23
	v_cvt_i32_f32_e32 v27, v34
	v_mul_f32_e32 v6, v10, v6
	v_cmp_nlt_f32_e32 vcc, s92, v2
	v_cvt_pk_bf16_f32 v6, v6, v6
	v_ldexp_f32 v10, v23, v27
	global_store_short v[14:15], v6, off offset:32
	v_cndmask_b32_e32 v10, 0, v10, vcc
	v_cmp_ngt_f32_e32 vcc, s93, v2
	v_mul_f32_e32 v6, v7, v19
	v_mul_f32_e32 v6, v39, v6
	v_cndmask_b32_e32 v10, v230, v10, vcc
	v_add_f32_e32 v10, 1.0, v10
	v_div_scale_f32 v11, s[10:11], v10, v10, 1.0
	v_rcp_f32_e32 v23, v11
	s_nop 0
	v_fma_f32 v7, -v11, v23, 1.0
	v_fmac_f32_e32 v23, v7, v23
	v_div_scale_f32 v7, vcc, 1.0, v10, 1.0
	v_mul_f32_e32 v27, v7, v23
	v_fma_f32 v34, -v11, v27, v7
	v_fmac_f32_e32 v27, v34, v23
	v_fma_f32 v7, -v11, v27, v7
	v_mul_f32_e32 v11, s78, v145
	v_div_fmas_f32 v7, v7, v23, v27
	v_mul_f32_e32 v23, 0x3fb8aa3b, v11
	v_fma_f32 v27, v11, s17, -v23
	v_rndne_f32_e32 v34, v23
	v_fmac_f32_e32 v27, 0x32a5705f, v11
	v_sub_f32_e32 v23, v23, v34
	v_add_f32_e32 v23, v23, v27
	v_exp_f32_e32 v23, v23
	v_cvt_i32_f32_e32 v27, v34
	v_div_fixup_f32 v7, v7, v10, 1.0
	v_mul_f32_e32 v2, v7, v2
	v_mul_f32_e32 v2, v6, v2
	v_ldexp_f32 v6, v23, v27
	v_cmp_ngt_f32_e32 vcc, s21, v11
	v_cvt_pk_bf16_f32 v2, v2, v2
	global_store_short v[14:15], v2, off offset:64
	v_mul_f32_e32 v2, v3, v19
	v_cndmask_b32_e32 v6, 0, v6, vcc
	v_cmp_nlt_f32_e32 vcc, s22, v11
	v_mul_f32_e32 v2, v26, v2
	s_nop 0
	v_cndmask_b32_e32 v6, v230, v6, vcc
	v_fmac_f32_e32 v16, v6, v20
	v_add_f32_e32 v7, 0, v16
	v_fmac_f32_e32 v12, v6, v24
	v_add_f32_e32 v7, v7, v12
	v_fmac_f32_e32 v8, v6, v28
	v_add_f32_e32 v7, v7, v8
	v_fmac_f32_e32 v4, v6, v32
	v_add_f32_e32 v6, v7, v4
	ds_bpermute_b32 v7, v36, v6
	s_waitcnt vmcnt(3)
	v_lshlrev_b32_e32 v20, 16, v31
	v_mul_f32_e32 v10, 0xbfb8aa3b, v20
	v_fma_f32 v11, v20, s83, -v10
	v_rndne_f32_e32 v23, v10
	s_waitcnt lgkmcnt(0)
; __device__ __forceinline__ unsigned cvt_pk_bf16(float lo, float hi) { unsigned r; asm("v_cvt_pk_bf16_f32 %0, %1, %2" : "=v"(r) : "v"(lo), "v"(hi)); return r; }
; __device__ __forceinline__ float sigmoidf_(float x) { return 1.f / (1.f + expf(-x)); }
; __device__ __forceinline__ float bf2f(unsigned short x) { return __uint_as_float(((unsigned)x) << 16); }
; __device__ __forceinline__ void ret_out_unit(const Frame& F, int l, int unit) {
;     ...
;     for (int j = 0; j < 4; ++j) {
;         const int i = i0 + fq * 4 + j; const float qd = expf((float)(i + 1) * lg);
;         float o[4], sm = 0.f;
; #pragma unroll
;         for (int dt = 0; dt < 4; ++dt) { o[dt] = acc1[dt][j] + qd * acc2[dt][j]; sm += o[dt]; }
;         sm += __shfl_xor(sm, 1); sm += __shfl_xor(sm, 2); sm += __shfl_xor(sm, 4); sm += __shfl_xor(sm, 8);
;         const float mean = sm * (1.f / 64.f); float vs = 0.f;
; #pragma unroll
;         for (int dt = 0; dt < 4; ++dt) { o[dt] -= mean; vs += o[dt] * o[dt]; }
;         vs += __shfl_xor(vs, 1); vs += __shfl_xor(vs, 2); vs += __shfl_xor(vs, 4); vs += __shfl_xor(vs, 8);
;         const float rstd = 1.f / sqrtf(vs * (1.f / 64.f) + LN_EPS);
;         const size_t tok = (size_t)b * S + n * 128 + i;
; #pragma unroll
;         for (int dt = 0; dt < 4; ++dt) { const int e = 16 * dt + fr;
;             const float rg = bf2f(((const bf16*)(F.ws + WS_RG))[tok * 256 + h * 64 + e]);
;             const float yv = o[dt] * rstd * gnw[e] * (rg * sigmoidf_(rg));
;             ((bf16*)(F.ws + WS_Y))[tok * D + h * 64 + e] = (bf16)(cvt_pk_bf16(yv, yv) & 0xffffu); }
	v_add_f32_e32 v6, v6, v7
	ds_bpermute_b32 v7, v37, v6
	v_fmac_f32_e32 v11, 0xb2a5705f, v20
	v_sub_f32_e32 v10, v10, v23
	v_add_f32_e32 v10, v10, v11
	v_exp_f32_e32 v24, v10
	s_waitcnt lgkmcnt(0)
	v_add_f32_e32 v27, v6, v7
	v_lshl_add_u64 v[6:7], s[44:45], 0, v[134:135]
	v_lshlrev_b64 v[10:11], 9, v[6:7]
	v_lshl_add_u64 v[10:11], s[46:47], 0, v[10:11]
	v_lshl_add_u64 v[10:11], v[10:11], 0, v[198:199]
	global_load_ushort v31, v[10:11], off nt
	global_load_ushort v32, v[10:11], off offset:32 nt
	ds_bpermute_b32 v28, v30, v27
	v_cvt_i32_f32_e32 v23, v23
	v_cmp_nlt_f32_e32 vcc, s92, v20
	s_waitcnt lgkmcnt(0)
	v_add_f32_e32 v27, v27, v28
	ds_bpermute_b32 v28, v38, v27
	v_ldexp_f32 v3, v24, v23
	v_cndmask_b32_e32 v3, 0, v3, vcc
	v_cmp_ngt_f32_e32 vcc, s93, v20
	s_waitcnt lgkmcnt(0)
	v_add_f32_e32 v19, v27, v28
	v_fmac_f32_e32 v12, 0xbc800000, v19
	v_fmac_f32_e32 v16, 0xbc800000, v19
	v_mul_f32_e32 v23, v12, v12
	v_fmac_f32_e32 v23, v16, v16
	v_fmac_f32_e32 v8, 0xbc800000, v19
	v_fmac_f32_e32 v23, v8, v8
	v_fmac_f32_e32 v4, 0xbc800000, v19
	v_fmac_f32_e32 v23, v4, v4
	ds_bpermute_b32 v19, v36, v23
	v_cndmask_b32_e32 v3, v230, v3, vcc
	v_add_f32_e32 v3, 1.0, v3
	v_div_scale_f32 v24, s[10:11], v3, v3, 1.0
	v_rcp_f32_e32 v27, v24
	s_waitcnt lgkmcnt(0)
	v_add_f32_e32 v19, v23, v19
	ds_bpermute_b32 v23, v37, v19
	v_fma_f32 v28, -v24, v27, 1.0
	v_fmac_f32_e32 v27, v28, v27
	v_div_scale_f32 v28, vcc, 1.0, v3, 1.0
	v_mul_f32_e32 v34, v28, v27
	s_waitcnt lgkmcnt(0)
	v_add_f32_e32 v19, v19, v23
	v_fma_f32 v35, -v24, v34, v28
	ds_bpermute_b32 v23, v30, v19
	v_fmac_f32_e32 v34, v35, v27
	v_fma_f32 v24, -v24, v34, v28
	v_div_fmas_f32 v24, v24, v27, v34
	v_div_fixup_f32 v3, v24, v3, 1.0
	v_mul_f32_e32 v3, v3, v20
	s_waitcnt lgkmcnt(0)
	v_add_f32_e32 v19, v19, v23
	v_mul_f32_e32 v2, v2, v3
	ds_bpermute_b32 v23, v38, v19
	v_cvt_pk_bf16_f32 v2, v2, v2
	global_store_short v[14:15], v2, off offset:96
	global_load_ushort v14, v[10:11], off offset:64 nt
	s_waitcnt lgkmcnt(0)
	v_add_f32_e32 v19, v19, v23
	v_fmamk_f32 v19, v19, 0x3c800000, v226
	v_mul_f32_e32 v23, 0x4f800000, v19
	v_cmp_gt_f32_e64 s[40:41], s2, v19
	global_load_ushort v10, v[10:11], off offset:96 nt
	s_waitcnt vmcnt(4)
	v_lshlrev_b32_e32 v11, 16, v31
	v_cndmask_b32_e64 v19, v19, v23, s[40:41]
	v_sqrt_f32_e32 v23, v19
	s_nop 0
	v_add_u32_e32 v20, -1, v23
	v_fma_f32 v24, -v20, v23, v19
	v_cmp_ge_f32_e32 vcc, 0, v24
	v_add_u32_e32 v24, 1, v23
	s_nop 0
	v_cndmask_b32_e32 v20, v23, v20, vcc
	v_fma_f32 v23, -v24, v23, v19
	v_cmp_lt_f32_e32 vcc, 0, v23
	s_nop 1
	v_cndmask_b32_e32 v20, v20, v24, vcc
	v_mul_f32_e32 v23, 0x37800000, v20
	v_cndmask_b32_e64 v20, v20, v23, s[40:41]
	v_cmp_class_f32_e32 vcc, v19, v227
	s_nop 1
	v_cndmask_b32_e32 v19, v20, v19, vcc
	v_div_scale_f32 v20, s[10:11], v19, v19, 1.0
	v_rcp_f32_e32 v23, v20
	s_nop 0
	v_fma_f32 v2, -v20, v23, 1.0
	v_fmac_f32_e32 v23, v2, v23
	v_div_scale_f32 v2, vcc, 1.0, v19, 1.0
	v_mul_f32_e32 v3, v2, v23
	v_fma_f32 v15, -v20, v3, v2
	v_fmac_f32_e32 v3, v15, v23
	v_mul_f32_e32 v15, 0xbfb8aa3b, v11
	v_fma_f32 v2, -v20, v3, v2
	v_fma_f32 v20, v11, s83, -v15
	v_rndne_f32_e32 v24, v15
	v_fmac_f32_e32 v20, 0xb2a5705f, v11
	v_sub_f32_e32 v15, v15, v24
	v_add_f32_e32 v15, v15, v20
	v_exp_f32_e32 v15, v15
	v_cvt_i32_f32_e32 v20, v24
	v_div_fmas_f32 v2, v2, v23, v3
	v_div_fixup_f32 v19, v2, v19, 1.0
	v_lshlrev_b64 v[2:3], 11, v[6:7]
	v_ldexp_f32 v6, v15, v20
	v_cmp_nlt_f32_e32 vcc, s92, v11
	v_mul_f32_e32 v16, v16, v19
	v_mul_f32_e32 v16, v18, v16
	v_cndmask_b32_e32 v6, 0, v6, vcc
	v_cmp_ngt_f32_e32 vcc, s93, v11
	v_lshl_add_u64 v[2:3], s[42:43], 0, v[2:3]
	v_lshl_add_u64 v[2:3], v[2:3], 0, v[198:199]
	v_cndmask_b32_e32 v6, v230, v6, vcc
	v_add_f32_e32 v6, 1.0, v6
	v_div_scale_f32 v7, s[10:11], v6, v6, 1.0
	v_rcp_f32_e32 v15, v7
	v_mul_f32_e32 v4, v4, v19
	v_mul_f32_e32 v4, v26, v4
	v_fma_f32 v20, -v7, v15, 1.0
	v_fmac_f32_e32 v15, v20, v15
	v_div_scale_f32 v20, vcc, 1.0, v6, 1.0
	v_mul_f32_e32 v23, v20, v15
	v_fma_f32 v24, -v7, v23, v20
	v_fmac_f32_e32 v23, v24, v15
	v_fma_f32 v7, -v7, v23, v20
	v_div_fmas_f32 v7, v7, v15, v23
	v_div_fixup_f32 v6, v7, v6, 1.0
	s_waitcnt vmcnt(3)
	v_lshlrev_b32_e32 v7, 16, v32
	v_mul_f32_e32 v6, v6, v11
	v_mul_f32_e32 v11, 0xbfb8aa3b, v7
	v_fma_f32 v15, v7, s83, -v11
	v_rndne_f32_e32 v20, v11
	v_fmac_f32_e32 v15, 0xb2a5705f, v7
	v_sub_f32_e32 v11, v11, v20
	v_add_f32_e32 v11, v11, v15
	v_exp_f32_e32 v11, v11
	v_cvt_i32_f32_e32 v15, v20
	v_cmp_nlt_f32_e32 vcc, s92, v7
	v_mul_f32_e32 v6, v6, v16
	v_cvt_pk_bf16_f32 v6, v6, v6
	v_ldexp_f32 v11, v11, v15
	v_cndmask_b32_e32 v11, 0, v11, vcc
	v_cmp_ngt_f32_e32 vcc, s93, v7
	global_store_short v[2:3], v6, off
	v_mul_f32_e32 v6, v12, v19
	v_cndmask_b32_e32 v11, v230, v11, vcc
	v_add_f32_e32 v11, 1.0, v11
	v_div_scale_f32 v15, s[10:11], v11, v11, 1.0
	v_rcp_f32_e32 v16, v15
	v_mul_f32_e32 v6, v22, v6
	v_fma_f32 v12, -v15, v16, 1.0
	v_fmac_f32_e32 v16, v12, v16
	v_div_scale_f32 v12, vcc, 1.0, v11, 1.0
	v_mul_f32_e32 v20, v12, v16
	v_fma_f32 v23, -v15, v20, v12
	v_fmac_f32_e32 v20, v23, v16
	v_fma_f32 v12, -v15, v20, v12
	v_div_fmas_f32 v12, v12, v16, v20
	v_div_fixup_f32 v11, v12, v11, 1.0
	s_waitcnt vmcnt(2)
; __device__ __forceinline__ unsigned cvt_pk_bf16(float lo, float hi) { unsigned r; asm("v_cvt_pk_bf16_f32 %0, %1, %2" : "=v"(r) : "v"(lo), "v"(hi)); return r; }
; __device__ __forceinline__ float sigmoidf_(float x) { return 1.f / (1.f + expf(-x)); }
; __device__ __forceinline__ float bf2f(unsigned short x) { return __uint_as_float(((unsigned)x) << 16); }
; __device__ __forceinline__ void ret_out_unit(const Frame& F, int l, int unit) {
;     ...
;     for (int j = 0; j < 4; ++j) {
;         const int i = i0 + fq * 4 + j; const float qd = expf((float)(i + 1) * lg);
;         float o[4], sm = 0.f;
; #pragma unroll
;         for (int dt = 0; dt < 4; ++dt) { o[dt] = acc1[dt][j] + qd * acc2[dt][j]; sm += o[dt]; }
;         sm += __shfl_xor(sm, 1); sm += __shfl_xor(sm, 2); sm += __shfl_xor(sm, 4); sm += __shfl_xor(sm, 8);
;         const float mean = sm * (1.f / 64.f); float vs = 0.f;
; #pragma unroll
;         for (int dt = 0; dt < 4; ++dt) { o[dt] -= mean; vs += o[dt] * o[dt]; }
;         vs += __shfl_xor(vs, 1); vs += __shfl_xor(vs, 2); vs += __shfl_xor(vs, 4); vs += __shfl_xor(vs, 8);
;         const float rstd = 1.f / sqrtf(vs * (1.f / 64.f) + LN_EPS);
;         const size_t tok = (size_t)b * S + n * 128 + i;
; #pragma unroll
;         for (int dt = 0; dt < 4; ++dt) { const int e = 16 * dt + fr;
;             const float rg = bf2f(((const bf16*)(F.ws + WS_RG))[tok * 256 + h * 64 + e]);
;             const float yv = o[dt] * rstd * gnw[e] * (rg * sigmoidf_(rg));
;             ((bf16*)(F.ws + WS_Y))[tok * D + h * 64 + e] = (bf16)(cvt_pk_bf16(yv, yv) & 0xffffu); }
	v_lshlrev_b32_e32 v12, 16, v14
	v_mul_f32_e32 v14, 0xbfb8aa3b, v12
	v_fma_f32 v15, v12, s83, -v14
	v_rndne_f32_e32 v16, v14
	v_fmac_f32_e32 v15, 0xb2a5705f, v12
	v_sub_f32_e32 v14, v14, v16
	v_add_f32_e32 v14, v14, v15
	v_exp_f32_e32 v14, v14
	v_cvt_i32_f32_e32 v15, v16
	v_mul_f32_e32 v7, v11, v7
	v_mul_f32_e32 v6, v7, v6
	v_cmp_nlt_f32_e32 vcc, s92, v12
	v_ldexp_f32 v7, v14, v15
	v_cvt_pk_bf16_f32 v6, v6, v6
	global_store_short v[2:3], v6, off offset:32
	v_cndmask_b32_e32 v7, 0, v7, vcc
	v_cmp_ngt_f32_e32 vcc, s93, v12
	v_mul_f32_e32 v6, v8, v19
	v_mul_f32_e32 v6, v39, v6
	v_cndmask_b32_e32 v7, v230, v7, vcc
	v_add_f32_e32 v7, 1.0, v7
	v_div_scale_f32 v11, s[10:11], v7, v7, 1.0
	v_rcp_f32_e32 v14, v11
	s_nop 0
	v_fma_f32 v8, -v11, v14, 1.0
	v_fmac_f32_e32 v14, v8, v14
	v_div_scale_f32 v8, vcc, 1.0, v7, 1.0
	v_mul_f32_e32 v15, v8, v14
	v_fma_f32 v16, -v11, v15, v8
	v_fmac_f32_e32 v15, v16, v14
	v_fma_f32 v8, -v11, v15, v8
	v_mul_f32_e32 v11, s78, v146
	v_div_fmas_f32 v8, v8, v14, v15
	v_mul_f32_e32 v14, 0x3fb8aa3b, v11
	v_fma_f32 v15, v11, s17, -v14
	v_rndne_f32_e32 v16, v14
	v_fmac_f32_e32 v15, 0x32a5705f, v11
	v_sub_f32_e32 v14, v14, v16
	v_add_f32_e32 v14, v14, v15
	v_exp_f32_e32 v14, v14
	v_cvt_i32_f32_e32 v15, v16
	v_div_fixup_f32 v7, v8, v7, 1.0
	v_mul_f32_e32 v7, v7, v12
	v_mul_f32_e32 v8, v6, v7
	v_ldexp_f32 v6, v14, v15
	v_cmp_ngt_f32_e32 vcc, s21, v11
	s_waitcnt vmcnt(2)
	v_lshlrev_b32_e32 v12, 16, v10
	v_mul_f32_e32 v10, 0xbfb8aa3b, v12
	v_cndmask_b32_e32 v6, 0, v6, vcc
	v_cmp_nlt_f32_e32 vcc, s22, v11
	v_fma_f32 v11, v12, s83, -v10
	v_rndne_f32_e32 v14, v10
	v_cndmask_b32_e32 v6, v230, v6, vcc
	v_fmac_f32_e32 v17, v6, v21
	v_add_f32_e32 v7, 0, v17
	v_fmac_f32_e32 v13, v6, v25
	v_add_f32_e32 v7, v7, v13
	v_fmac_f32_e32 v9, v6, v29
	v_add_f32_e32 v7, v7, v9
	v_fmac_f32_e32 v5, v6, v33
	v_add_f32_e32 v6, v7, v5
	ds_bpermute_b32 v7, v36, v6
	v_fmac_f32_e32 v11, 0xb2a5705f, v12
	v_sub_f32_e32 v10, v10, v14
	v_add_f32_e32 v10, v10, v11
	v_exp_f32_e32 v15, v10
	s_waitcnt lgkmcnt(0)
	v_add_f32_e32 v6, v6, v7
	ds_bpermute_b32 v7, v37, v6
	v_cvt_i32_f32_e32 v14, v14
	v_cvt_pk_bf16_f32 v8, v8, v8
	global_store_short v[2:3], v8, off offset:64
	v_cmp_nlt_f32_e32 vcc, s92, v12
	s_waitcnt lgkmcnt(0)
	v_add_f32_e32 v16, v6, v7
	v_lshl_add_u64 v[6:7], s[44:45], 0, v[136:137]
	v_lshlrev_b64 v[10:11], 9, v[6:7]
	v_lshl_add_u64 v[10:11], s[46:47], 0, v[10:11]
	v_lshl_add_u64 v[10:11], v[10:11], 0, v[198:199]
	global_load_ushort v21, v[10:11], off nt
	global_load_ushort v23, v[10:11], off offset:32 nt
	ds_bpermute_b32 v20, v30, v16
	v_ldexp_f32 v8, v15, v14
	v_cndmask_b32_e32 v8, 0, v8, vcc
	v_cmp_ngt_f32_e32 vcc, s93, v12
	s_waitcnt lgkmcnt(0)
	v_add_f32_e32 v16, v16, v20
	ds_bpermute_b32 v20, v38, v16
	v_cndmask_b32_e32 v8, v230, v8, vcc
	v_add_f32_e32 v8, 1.0, v8
	s_waitcnt lgkmcnt(0)
	v_add_f32_e32 v14, v16, v20
	v_fmac_f32_e32 v13, 0xbc800000, v14
	v_fmac_f32_e32 v17, 0xbc800000, v14
	v_mul_f32_e32 v15, v13, v13
	v_fmac_f32_e32 v15, v17, v17
	v_fmac_f32_e32 v9, 0xbc800000, v14
	v_fmac_f32_e32 v15, v9, v9
	v_fmac_f32_e32 v5, 0xbc800000, v14
	v_fmac_f32_e32 v15, v5, v5
	ds_bpermute_b32 v14, v36, v15
	v_div_scale_f32 v16, s[10:11], v8, v8, 1.0
	v_rcp_f32_e32 v19, v16
	s_waitcnt lgkmcnt(0)
	v_add_f32_e32 v14, v15, v14
	ds_bpermute_b32 v15, v37, v14
	v_fma_f32 v20, -v16, v19, 1.0
	v_fmac_f32_e32 v19, v20, v19
	v_div_scale_f32 v20, vcc, 1.0, v8, 1.0
	s_waitcnt lgkmcnt(0)
	v_add_f32_e32 v14, v14, v15
	ds_bpermute_b32 v15, v30, v14
	v_mul_f32_e32 v24, v20, v19
	v_fma_f32 v25, -v16, v24, v20
	v_fmac_f32_e32 v24, v25, v19
	v_fma_f32 v16, -v16, v24, v20
	s_waitcnt lgkmcnt(0)
	v_add_f32_e32 v14, v14, v15
	ds_bpermute_b32 v15, v38, v14
	v_div_fmas_f32 v16, v16, v19, v24
	v_div_fixup_f32 v8, v16, v8, 1.0
	v_mul_f32_e32 v8, v8, v12
	v_mul_f32_e32 v4, v4, v8
	s_waitcnt lgkmcnt(0)
	v_add_f32_e32 v14, v14, v15
	v_fmamk_f32 v14, v14, 0x3c800000, v226
	v_cvt_pk_bf16_f32 v4, v4, v4
	v_mul_f32_e32 v15, 0x4f800000, v14
	v_cmp_gt_f32_e64 s[40:41], s2, v14
	global_store_short v[2:3], v4, off offset:96
	global_load_ushort v4, v[10:11], off offset:64 nt
	v_cndmask_b32_e64 v14, v14, v15, s[40:41]
	v_sqrt_f32_e32 v15, v14
	s_nop 0
	v_add_u32_e32 v12, -1, v15
	v_fma_f32 v16, -v12, v15, v14
	v_cmp_ge_f32_e32 vcc, 0, v16
	v_add_u32_e32 v16, 1, v15
	s_nop 0
	v_cndmask_b32_e32 v12, v15, v12, vcc
	v_fma_f32 v15, -v16, v15, v14
	v_cmp_lt_f32_e32 vcc, 0, v15
	s_nop 1
	v_cndmask_b32_e32 v12, v12, v16, vcc
	v_mul_f32_e32 v15, 0x37800000, v12
	v_cndmask_b32_e64 v12, v12, v15, s[40:41]
	v_cmp_class_f32_e32 vcc, v14, v227
	s_nop 1
	v_cndmask_b32_e32 v12, v12, v14, vcc
	v_div_scale_f32 v14, s[10:11], v12, v12, 1.0
	v_rcp_f32_e32 v15, v14
	s_nop 0
	v_fma_f32 v2, -v14, v15, 1.0
	v_fmac_f32_e32 v15, v2, v15
	v_div_scale_f32 v2, vcc, 1.0, v12, 1.0
	v_mul_f32_e32 v3, v2, v15
	v_fma_f32 v8, -v14, v3, v2
	v_fmac_f32_e32 v3, v8, v15
	global_load_ushort v8, v[10:11], off offset:96 nt
	s_waitcnt vmcnt(4)
	v_lshlrev_b32_e32 v10, 16, v21
	v_mul_f32_e32 v11, 0xbfb8aa3b, v10
	v_fma_f32 v2, -v14, v3, v2
	v_fma_f32 v14, v10, s83, -v11
	v_rndne_f32_e32 v16, v11
	v_fmac_f32_e32 v14, 0xb2a5705f, v10
	v_sub_f32_e32 v11, v11, v16
	v_add_f32_e32 v11, v11, v14
	v_exp_f32_e32 v11, v11
	v_cvt_i32_f32_e32 v14, v16
	v_div_fmas_f32 v2, v2, v15, v3
	v_div_fixup_f32 v12, v2, v12, 1.0
	v_lshlrev_b64 v[2:3], 11, v[6:7]
	v_ldexp_f32 v6, v11, v14
	v_cmp_nlt_f32_e32 vcc, s92, v10
	v_mul_f32_e32 v14, v17, v12
	v_mul_f32_e32 v14, v18, v14
	v_cndmask_b32_e32 v6, 0, v6, vcc
	v_cmp_ngt_f32_e32 vcc, s93, v10
	v_lshl_add_u64 v[2:3], s[42:43], 0, v[2:3]
	v_lshl_add_u64 v[2:3], v[2:3], 0, v[198:199]
	v_cndmask_b32_e32 v6, v230, v6, vcc
	v_add_f32_e32 v6, 1.0, v6
	v_div_scale_f32 v7, s[10:11], v6, v6, 1.0
	v_rcp_f32_e32 v11, v7
	s_waitcnt vmcnt(1)
; #define LAS __attribute__((address_space(3)))
; __device__ __forceinline__ unsigned cvt_pk_bf16(float lo, float hi) { unsigned r; asm("v_cvt_pk_bf16_f32 %0, %1, %2" : "=v"(r) : "v"(lo), "v"(hi)); return r; }
; __device__ __forceinline__ void ret_stage(const Frame& F, int b, int h, int n, bool full, float lg) {
;     LAS unsigned char* L = F.lds;
;     const int tk = F.tid >> 2, part = F.tid & 3;
;     const size_t rowoff = (((size_t)b * 4 + h) * S + n * 128 + tk) * 64 + part * 16;
;     const u32x4* kp = (const u32x4*)((const bf16*)(F.ws + WS_PRK) + rowoff);
;     const u32x4* vp = (const u32x4*)((const bf16*)(F.ws + WS_PRV) + rowoff);
;     const u32x4 k0 = kp[0], k1 = kp[1], v0 = vp[0], v1 = vp[1];
;     if (full) { const u32x4* qp = (const u32x4*)((const bf16*)(F.ws + WS_PRQ) + rowoff);
;         const u32x4 q0 = qp[0], q1 = qp[1];
;         *(LAS u32x4*)(L + RL_Q + tk * 128 + part * 32) = q0; *(LAS u32x4*)(L + RL_Q + tk * 128 + part * 32 + 16) = q1;
;         *(LAS u32x4*)(L + RL_K + tk * 128 + part * 32) = k0; *(LAS u32x4*)(L + RL_K + tk * 128 + part * 32 + 16) = k1; }
; __device__ __forceinline__ void ret_out_unit(const Frame& F, int l, int unit) {
;     ...
;     for (int j = 0; j < 4; ++j) {
;         const int i = i0 + fq * 4 + j; const float qd = expf((float)(i + 1) * lg);
;         float o[4], sm = 0.f;
; #pragma unroll
;         for (int dt = 0; dt < 4; ++dt) { o[dt] = acc1[dt][j] + qd * acc2[dt][j]; sm += o[dt]; }
;         sm += __shfl_xor(sm, 1); sm += __shfl_xor(sm, 2); sm += __shfl_xor(sm, 4); sm += __shfl_xor(sm, 8);
;         const float mean = sm * (1.f / 64.f); float vs = 0.f;
; #pragma unroll
;         for (int dt = 0; dt < 4; ++dt) { o[dt] -= mean; vs += o[dt] * o[dt]; }
;         vs += __shfl_xor(vs, 1); vs += __shfl_xor(vs, 2); vs += __shfl_xor(vs, 4); vs += __shfl_xor(vs, 8);
;         const float rstd = 1.f / sqrtf(vs * (1.f / 64.f) + LN_EPS);
;         const size_t tok = (size_t)b * S + n * 128 + i;
; #pragma unroll
;         for (int dt = 0; dt < 4; ++dt) { const int e = 16 * dt + fr;
;             const float rg = bf2f(((const bf16*)(F.ws + WS_RG))[tok * 256 + h * 64 + e]);
;             const float yv = o[dt] * rstd * gnw[e] * (rg * sigmoidf_(rg));
;             ((bf16*)(F.ws + WS_Y))[tok * D + h * 64 + e] = (bf16)(cvt_pk_bf16(yv, yv) & 0xffffu); }
	v_lshlrev_b32_e32 v4, 16, v4
	v_fma_f32 v15, -v7, v11, 1.0
	v_fmac_f32_e32 v11, v15, v11
	v_div_scale_f32 v15, vcc, 1.0, v6, 1.0
	v_mul_f32_e32 v16, v15, v11
	v_fma_f32 v17, -v7, v16, v15
	v_fmac_f32_e32 v16, v17, v11
	v_fma_f32 v7, -v7, v16, v15
	v_div_fmas_f32 v7, v7, v11, v16
	v_div_fixup_f32 v6, v7, v6, 1.0
	v_lshlrev_b32_e32 v7, 16, v23
	v_mul_f32_e32 v6, v6, v10
	v_mul_f32_e32 v10, 0xbfb8aa3b, v7
	v_fma_f32 v11, v7, s83, -v10
	v_rndne_f32_e32 v15, v10
	v_fmac_f32_e32 v11, 0xb2a5705f, v7
	v_sub_f32_e32 v10, v10, v15
	v_add_f32_e32 v10, v10, v11
	v_exp_f32_e32 v10, v10
	v_cvt_i32_f32_e32 v11, v15
	v_cmp_nlt_f32_e32 vcc, s92, v7
	v_mul_f32_e32 v6, v6, v14
	v_cvt_pk_bf16_f32 v6, v6, v6
	v_ldexp_f32 v10, v10, v11
	v_cndmask_b32_e32 v10, 0, v10, vcc
	v_cmp_ngt_f32_e32 vcc, s93, v7
	global_store_short v[2:3], v6, off
	v_mul_f32_e32 v6, v13, v12
	v_cndmask_b32_e32 v10, v230, v10, vcc
	v_add_f32_e32 v10, 1.0, v10
	v_div_scale_f32 v11, s[10:11], v10, v10, 1.0
	v_rcp_f32_e32 v14, v11
	v_mul_f32_e32 v6, v22, v6
	s_waitcnt vmcnt(1)
	v_lshlrev_b32_e32 v8, 16, v8
	v_fma_f32 v13, -v11, v14, 1.0
	v_fmac_f32_e32 v14, v13, v14
	v_div_scale_f32 v13, vcc, 1.0, v10, 1.0
	v_mul_f32_e32 v15, v13, v14
	v_fma_f32 v16, -v11, v15, v13
	v_fmac_f32_e32 v15, v16, v14
	v_fma_f32 v11, -v11, v15, v13
	v_div_fmas_f32 v11, v11, v14, v15
	v_div_fixup_f32 v10, v11, v10, 1.0
	v_mul_f32_e32 v11, 0xbfb8aa3b, v4
	v_fma_f32 v13, v4, s83, -v11
	v_rndne_f32_e32 v14, v11
	v_fmac_f32_e32 v13, 0xb2a5705f, v4
	v_sub_f32_e32 v11, v11, v14
	v_add_f32_e32 v11, v11, v13
	v_exp_f32_e32 v11, v11
	v_cvt_i32_f32_e32 v13, v14
	v_mul_f32_e32 v7, v10, v7
	v_mul_f32_e32 v6, v7, v6
	v_cmp_nlt_f32_e32 vcc, s92, v4
	v_ldexp_f32 v7, v11, v13
	v_cvt_pk_bf16_f32 v6, v6, v6
	global_store_short v[2:3], v6, off offset:32
	v_cndmask_b32_e32 v7, 0, v7, vcc
	v_cmp_ngt_f32_e32 vcc, s93, v4
	v_mul_f32_e32 v6, v9, v12
	v_mul_f32_e32 v6, v39, v6
	v_cndmask_b32_e32 v7, v230, v7, vcc
	v_add_f32_e32 v7, 1.0, v7
	v_div_scale_f32 v10, s[10:11], v7, v7, 1.0
	v_rcp_f32_e32 v11, v10
	s_nop 0
	v_fma_f32 v9, -v10, v11, 1.0
	v_fmac_f32_e32 v11, v9, v11
	v_div_scale_f32 v9, vcc, 1.0, v7, 1.0
	v_mul_f32_e32 v13, v9, v11
	v_fma_f32 v14, -v10, v13, v9
	v_fmac_f32_e32 v13, v14, v11
	v_fma_f32 v9, -v10, v13, v9
	v_div_fmas_f32 v9, v9, v11, v13
	v_div_fixup_f32 v7, v9, v7, 1.0
	v_mul_f32_e32 v9, 0xbfb8aa3b, v8
	v_fma_f32 v10, v8, s83, -v9
	v_rndne_f32_e32 v11, v9
	v_fmac_f32_e32 v10, 0xb2a5705f, v8
	v_sub_f32_e32 v9, v9, v11
	v_add_f32_e32 v9, v9, v10
	v_exp_f32_e32 v9, v9
	v_cvt_i32_f32_e32 v10, v11
	v_mul_f32_e32 v4, v7, v4
	v_mul_f32_e32 v4, v6, v4
	v_cmp_nlt_f32_e32 vcc, s92, v8
	v_ldexp_f32 v6, v9, v10
	v_cvt_pk_bf16_f32 v4, v4, v4
	global_store_short v[2:3], v4, off offset:64
	v_cndmask_b32_e32 v6, 0, v6, vcc
	v_cmp_ngt_f32_e32 vcc, s93, v8
	v_mul_f32_e32 v4, v5, v12
	v_mul_f32_e32 v4, v26, v4
	v_cndmask_b32_e32 v6, v230, v6, vcc
	v_add_f32_e32 v6, 1.0, v6
	v_div_scale_f32 v7, s[10:11], v6, v6, 1.0
	v_rcp_f32_e32 v9, v7
	s_nop 0
	v_fma_f32 v5, -v7, v9, 1.0
	v_fmac_f32_e32 v9, v5, v9
	v_div_scale_f32 v5, vcc, 1.0, v6, 1.0
	v_mul_f32_e32 v10, v5, v9
	v_fma_f32 v11, -v7, v10, v5
	v_fmac_f32_e32 v10, v11, v9
	v_fma_f32 v5, -v7, v10, v5
	v_div_fmas_f32 v5, v5, v9, v10
	v_div_fixup_f32 v5, v5, v6, 1.0
	v_mul_f32_e32 v5, v5, v8
	v_mul_f32_e32 v4, v4, v5
	v_cvt_pk_bf16_f32 v4, v4, v4
	global_store_short v[2:3], v4, off offset:96
	s_cbranch_scc1 .LBB0_1595
.LBB0_1560:
	s_bfe_u32 s79, s77, 0x20004
	s_and_b32 s3, s77, 15
	s_ashr_i32 s72, s77, 6
	s_lshl_b32 s26, s79, 2
	s_getpc_b64 s[10:11]
	s_add_u32 s10, s10, c_log_gamma@rel32@lo+4
	s_addc_u32 s11, s11, c_log_gamma@rel32@hi+12
	s_load_dword s78, s[10:11], s26 offset:0x0
	s_ashr_i32 s73, s72, 31
	s_lshl_b32 s26, s79, 11
	s_lshl_b32 s34, s3, 7
	s_lshl_b64 s[10:11], s[72:73], 13
	s_or_b32 s26, s26, s34
	s_or_b32 s10, s10, s26
	v_lshl_add_u64 v[2:3], s[10:11], 0, v[122:123]
	v_lshlrev_b64 v[10:11], 7, v[2:3]
	v_lshl_or_b32 v10, v124, 1, v10
	v_lshl_add_u64 v[6:7], s[14:15], 0, v[10:11]
	v_lshl_add_u64 v[14:15], s[36:37], 0, v[10:11]
	s_waitcnt lgkmcnt(0)
	s_barrier
	v_lshl_add_u64 v[18:19], s[28:29], 0, v[10:11]
	global_load_dwordx4 v[2:5], v[6:7], off offset:16 nt
	s_nop 0
	global_load_dwordx4 v[6:9], v[6:7], off nt
	s_nop 0
	global_load_dwordx4 v[10:13], v[14:15], off offset:16 nt
	s_nop 0
	global_load_dwordx4 v[14:17], v[14:15], off nt
	global_load_dwordx4 v[26:29], v[18:19], off nt
	global_load_dwordx4 v[30:33], v[18:19], off offset:16 nt
	s_lshl_b64 s[10:11], s[72:73], 20
	s_add_u32 s10, s4, s10
	s_addc_u32 s11, s5, s11
	s_lshl_b32 s26, s79, 18
	s_add_u32 s10, s10, s26
	s_addc_u32 s11, s11, 0
	s_cmp_eq_u32 s3, 0
	s_cselect_b64 s[26:27], -1, 0
	v_lshl_add_u64 v[140:141], v[126:127], 2, s[10:11]
	s_and_b64 vcc, exec, s[26:27]
	v_mov_b32_e32 v22, 0
	v_mov_b32_e32 v23, 0
	v_mov_b32_e32 v24, 0
	v_mov_b32_e32 v25, 0
	s_waitcnt vmcnt(2)
	ds_write_b128 v154, v[14:17]
	ds_write_b128 v154, v[10:13] offset:16
	ds_write_b128 v154, v[6:9] offset:16384
	ds_write_b128 v154, v[2:5] offset:16400
	v_mov_b32_e32 v14, 0
	v_mov_b32_e32 v15, 0
	v_mov_b32_e32 v16, 0
	v_mov_b32_e32 v17, 0
	s_waitcnt vmcnt(1)
	ds_write_b16 v155, v26 offset:49152
	ds_write_b16_d16_hi v156, v26 offset:49408
	ds_write_b16 v155, v27 offset:49664
	ds_write_b16_d16_hi v156, v27 offset:49920
	ds_write_b16 v155, v28 offset:50176
	ds_write_b16_d16_hi v156, v28 offset:50432
	ds_write_b16 v155, v29 offset:50688
	ds_write_b16_d16_hi v156, v29 offset:50944
	s_waitcnt vmcnt(0)
	ds_write_b16 v155, v30 offset:51200
	ds_write_b16_d16_hi v156, v30 offset:51456
	ds_write_b16 v155, v31 offset:51712
	ds_write_b16_d16_hi v156, v31 offset:51968
	ds_write_b16 v155, v32 offset:52224
	ds_write_b16_d16_hi v156, v32 offset:52480
	ds_write_b16 v155, v33 offset:52736
	ds_write_b16_d16_hi v156, v33 offset:52992
	v_mov_b32_e32 v2, 0
	s_cbranch_vccnz .LBB0_1562
	global_load_dwordx4 v[14:17], v[140:141], off
	global_load_dwordx4 v[22:25], v[140:141], off offset:16
